# pair-wise K-slice issue with the first wave group's burst moved earlier in the odd step (after 4 MFMAs) for more separation from the second group's burst
# speedup vs baseline: 1.0057x; 1.0057x over previous
.Lg0_Ew:
.Lg0_O:
	s_waitcnt lgkmcnt(0)
	s_barrier
	ds_read_b128 v[128:131], v254 offset:16384
	ds_read_b128 v[132:135], v254 offset:17408
	ds_read_b128 v[148:151], v152
	ds_read_b128 v[144:147], v152 offset:1024
	v_mfma_f32_16x16x32_bf16 v[24:27], v[246:249], v[168:171], v[24:27]
	v_mfma_f32_16x16x32_bf16 v[20:23], v[250:253], v[168:171], v[20:23]
	v_mfma_f32_16x16x32_bf16 v[16:19], v[136:139], v[168:171], v[16:19]
	v_mfma_f32_16x16x32_bf16 v[12:15], v[140:143], v[168:171], v[12:15]
	s_cmp_lt_u32 s35, s17
	s_cbranch_scc0 .Lg0_O_sa
	s_sub_u32 s8, s8, 64
	s_subb_u32 s9, s9, 0
	s_cmp_gt_i32 s36, 0
	s_cselect_b32 s12, -1, 4
	s_add_i32 s12, s12, s36
	s_lshl_b32 s12, s12, 15
	s_add_i32 s12, s12, s16
	s_cmp_gt_i32 s36, 1
	s_cselect_b32 s10, -2, 3
	s_add_i32 s10, s10, s36
	s_lshl_b32 s10, s10, 15
	s_add_i32 s10, s10, s16
	s_mov_b32 m0, s10
	v_lshl_add_u64 v[168:169], v[160:161], 0, s[8:9]
	global_load_lds_dwordx4 v[168:169], off
	s_mov_b32 m0, s12
	v_lshl_add_u64 v[168:169], v[168:169], 0, 64
	global_load_lds_dwordx4 v[168:169], off
	s_add_u32 m0, s10, 0x2000
	v_lshl_add_u64 v[168:169], v[158:159], 0, s[8:9]
	global_load_lds_dwordx4 v[168:169], off
	s_add_u32 m0, s12, 0x2000
	v_lshl_add_u64 v[168:169], v[168:169], 0, 64
	global_load_lds_dwordx4 v[168:169], off
	s_add_u32 m0, s10, 0x4000
	v_lshl_add_u64 v[168:169], v[156:157], 0, s[8:9]
	global_load_lds_dwordx4 v[168:169], off
	s_add_u32 m0, s12, 0x4000
	v_lshl_add_u64 v[168:169], v[168:169], 0, 64
	global_load_lds_dwordx4 v[168:169], off
	s_add_u32 m0, s10, 0x6000
	v_lshl_add_u64 v[168:169], v[154:155], 0, s[8:9]
	global_load_lds_dwordx4 v[168:169], off
	s_add_u32 m0, s12, 0x6000
	v_lshl_add_u64 v[168:169], v[168:169], 0, 64
	global_load_lds_dwordx4 v[168:169], off
	s_add_u32 s8, s8, 64
	s_addc_u32 s9, s9, 0
.Lg0_O_sa:
	v_mfma_f32_16x16x32_bf16 v[8:11], v[246:249], v[172:175], v[8:11]
	v_mfma_f32_16x16x32_bf16 v[4:7], v[250:253], v[172:175], v[4:7]
	v_mfma_f32_16x16x32_bf16 v[0:3], v[136:139], v[172:175], v[0:3]
	v_mfma_f32_16x16x32_bf16 v[36:39], v[140:143], v[172:175], v[36:39]
	ds_read_b128 v[136:139], v254 offset:18432
	ds_read_b128 v[140:143], v254 offset:19456
	ds_read_b128 v[168:171], v152 offset:2048
	ds_read_b128 v[172:175], v152 offset:3072
	s_waitcnt lgkmcnt(4)
	v_mfma_f32_16x16x32_bf16 v[124:127], v[128:131], v[148:151], v[124:127]
	v_mfma_f32_16x16x32_bf16 v[120:123], v[132:135], v[148:151], v[120:123]
	v_mfma_f32_16x16x32_bf16 v[108:111], v[128:131], v[144:147], v[108:111]
	v_mfma_f32_16x16x32_bf16 v[104:107], v[132:135], v[144:147], v[104:107]
	s_waitcnt lgkmcnt(2)
	v_mfma_f32_16x16x32_bf16 v[116:119], v[136:139], v[148:151], v[116:119]
	v_mfma_f32_16x16x32_bf16 v[112:115], v[140:143], v[148:151], v[112:115]
	v_mfma_f32_16x16x32_bf16 v[100:103], v[136:139], v[144:147], v[100:103]
	v_mfma_f32_16x16x32_bf16 v[96:99], v[140:143], v[144:147], v[96:99]
	s_waitcnt lgkmcnt(0)
	v_mfma_f32_16x16x32_bf16 v[92:95], v[128:131], v[168:171], v[92:95]
	ds_read_b128 v[144:147], v152 offset:4096
	ds_read_b128 v[148:151], v152 offset:5120
	v_mfma_f32_16x16x32_bf16 v[88:91], v[132:135], v[168:171], v[88:91]
	v_mfma_f32_16x16x32_bf16 v[84:87], v[136:139], v[168:171], v[84:87]
	v_mfma_f32_16x16x32_bf16 v[80:83], v[140:143], v[168:171], v[80:83]
	v_mfma_f32_16x16x32_bf16 v[76:79], v[128:131], v[172:175], v[76:79]
	v_mfma_f32_16x16x32_bf16 v[72:75], v[132:135], v[172:175], v[72:75]
	v_mfma_f32_16x16x32_bf16 v[68:71], v[136:139], v[172:175], v[68:71]
	v_mfma_f32_16x16x32_bf16 v[64:67], v[140:143], v[172:175], v[64:67]
	s_cmp_lt_u32 s35, s11
	s_cbranch_scc0 .Lg0_O_sb
	s_sub_u32 s8, s8, 64
	s_subb_u32 s9, s9, 0
	s_cmp_gt_i32 s36, 0
	s_cselect_b32 s12, -1, 4
	s_add_i32 s12, s12, s36
	s_lshl_b32 s12, s12, 15
	s_add_i32 s12, s12, s16
	s_cmp_gt_i32 s36, 1
	s_cselect_b32 s10, -2, 3
	s_add_i32 s10, s10, s36
	s_lshl_b32 s10, s10, 15
	s_add_i32 s10, s10, s16
	s_mov_b32 m0, s10
	v_lshl_add_u64 v[168:169], v[160:161], 0, s[8:9]
	global_load_lds_dwordx4 v[168:169], off
	s_mov_b32 m0, s12
	v_lshl_add_u64 v[168:169], v[168:169], 0, 64
	global_load_lds_dwordx4 v[168:169], off
	s_add_u32 m0, s10, 0x2000
	v_lshl_add_u64 v[168:169], v[158:159], 0, s[8:9]
	global_load_lds_dwordx4 v[168:169], off
	s_add_u32 m0, s12, 0x2000
	v_lshl_add_u64 v[168:169], v[168:169], 0, 64
	global_load_lds_dwordx4 v[168:169], off
	s_add_u32 m0, s10, 0x4000
	v_lshl_add_u64 v[168:169], v[156:157], 0, s[8:9]
	global_load_lds_dwordx4 v[168:169], off
	s_add_u32 m0, s12, 0x4000
	v_lshl_add_u64 v[168:169], v[168:169], 0, 64
	global_load_lds_dwordx4 v[168:169], off
	s_add_u32 m0, s10, 0x6000
	v_lshl_add_u64 v[168:169], v[154:155], 0, s[8:9]
	global_load_lds_dwordx4 v[168:169], off
	s_add_u32 m0, s12, 0x6000
	v_lshl_add_u64 v[168:169], v[168:169], 0, 64
	global_load_lds_dwordx4 v[168:169], off
	s_add_u32 s8, s8, 64
	s_addc_u32 s9, s9, 0

.Lg1_Ew:
.Lg1_O:
	s_waitcnt lgkmcnt(0)
	s_barrier
	ds_read_b128 v[130:133], v254 offset:16384
	ds_read_b128 v[134:137], v254 offset:17408
	ds_read_b128 v[150:153], v64
	ds_read_b128 v[146:149], v64 offset:1024
	v_mfma_f32_16x16x32_bf16 v[28:31], v[246:249], v[200:203], v[28:31]
	v_mfma_f32_16x16x32_bf16 v[24:27], v[250:253], v[200:203], v[24:27]
	v_mfma_f32_16x16x32_bf16 v[20:23], v[138:141], v[200:203], v[20:23]
	v_mfma_f32_16x16x32_bf16 v[16:19], v[142:145], v[200:203], v[16:19]
	s_cmp_lt_u32 s25, s37
	s_cbranch_scc0 .Lg1_O_sa
	s_sub_u32 s0, s0, 64
	s_subb_u32 s1, s1, 0
	s_cmp_gt_i32 s60, 0
	s_cselect_b32 s30, -1, 4
	s_add_i32 s30, s30, s60
	s_lshl_b32 s30, s30, 15
	s_add_i32 s30, s30, s36
	s_cmp_gt_i32 s60, 1
	s_cselect_b32 s26, -2, 3
	s_add_i32 s26, s26, s60
	s_lshl_b32 s26, s26, 15
	s_add_i32 s26, s26, s36
	s_mov_b32 m0, s26
	v_lshl_add_u64 v[200:201], v[164:165], 0, s[0:1]
	global_load_lds_dwordx4 v[200:201], off
	s_mov_b32 m0, s30
	v_lshl_add_u64 v[200:201], v[200:201], 0, 64
	global_load_lds_dwordx4 v[200:201], off
	s_add_u32 m0, s26, 0x2000
	v_lshl_add_u64 v[200:201], v[162:163], 0, s[0:1]
	global_load_lds_dwordx4 v[200:201], off
	s_add_u32 m0, s30, 0x2000
	v_lshl_add_u64 v[200:201], v[200:201], 0, 64
	global_load_lds_dwordx4 v[200:201], off
	s_add_u32 m0, s26, 0x4000
	v_lshl_add_u64 v[200:201], v[160:161], 0, s[0:1]
	global_load_lds_dwordx4 v[200:201], off
	s_add_u32 m0, s30, 0x4000
	v_lshl_add_u64 v[200:201], v[200:201], 0, 64
	global_load_lds_dwordx4 v[200:201], off
	s_add_u32 m0, s26, 0x6000
	v_lshl_add_u64 v[200:201], v[158:159], 0, s[0:1]
	global_load_lds_dwordx4 v[200:201], off
	s_add_u32 m0, s30, 0x6000
	v_lshl_add_u64 v[200:201], v[200:201], 0, 64
	global_load_lds_dwordx4 v[200:201], off
	s_add_u32 s0, s0, 64
	s_addc_u32 s1, s1, 0
.Lg1_O_sa:
	v_mfma_f32_16x16x32_bf16 v[12:15], v[246:249], v[204:207], v[12:15]
	v_mfma_f32_16x16x32_bf16 v[8:11], v[250:253], v[204:207], v[8:11]
	v_mfma_f32_16x16x32_bf16 v[4:7], v[138:141], v[204:207], v[4:7]
	v_mfma_f32_16x16x32_bf16 v[0:3], v[142:145], v[204:207], v[0:3]
	ds_read_b128 v[138:141], v254 offset:18432
	ds_read_b128 v[142:145], v254 offset:19456
	ds_read_b128 v[200:203], v64 offset:2048
	ds_read_b128 v[204:207], v64 offset:3072
	s_waitcnt lgkmcnt(4)
	v_mfma_f32_16x16x32_bf16 v[126:129], v[130:133], v[150:153], v[126:129]
	v_mfma_f32_16x16x32_bf16 v[122:125], v[134:137], v[150:153], v[122:125]
	v_mfma_f32_16x16x32_bf16 v[110:113], v[130:133], v[146:149], v[110:113]
	v_mfma_f32_16x16x32_bf16 v[106:109], v[134:137], v[146:149], v[106:109]
	s_waitcnt lgkmcnt(2)
	v_mfma_f32_16x16x32_bf16 v[118:121], v[138:141], v[150:153], v[118:121]
	v_mfma_f32_16x16x32_bf16 v[114:117], v[142:145], v[150:153], v[114:117]
	v_mfma_f32_16x16x32_bf16 v[102:105], v[138:141], v[146:149], v[102:105]
	v_mfma_f32_16x16x32_bf16 v[98:101], v[142:145], v[146:149], v[98:101]
	s_waitcnt lgkmcnt(0)
	v_mfma_f32_16x16x32_bf16 v[94:97], v[130:133], v[200:203], v[94:97]
	ds_read_b128 v[146:149], v64 offset:4096
	ds_read_b128 v[150:153], v64 offset:5120
	v_mfma_f32_16x16x32_bf16 v[90:93], v[134:137], v[200:203], v[90:93]
	v_mfma_f32_16x16x32_bf16 v[86:89], v[138:141], v[200:203], v[86:89]
	v_mfma_f32_16x16x32_bf16 v[82:85], v[142:145], v[200:203], v[82:85]
	v_mfma_f32_16x16x32_bf16 v[78:81], v[130:133], v[204:207], v[78:81]
	v_mfma_f32_16x16x32_bf16 v[74:77], v[134:137], v[204:207], v[74:77]
	v_mfma_f32_16x16x32_bf16 v[70:73], v[138:141], v[204:207], v[70:73]
	v_mfma_f32_16x16x32_bf16 v[66:69], v[142:145], v[204:207], v[66:69]
	s_cmp_lt_u32 s25, s27
	s_cbranch_scc0 .Lg1_O_sb
	s_sub_u32 s0, s0, 64
	s_subb_u32 s1, s1, 0
	s_cmp_gt_i32 s60, 0
	s_cselect_b32 s30, -1, 4
	s_add_i32 s30, s30, s60
	s_lshl_b32 s30, s30, 15
	s_add_i32 s30, s30, s36
	s_cmp_gt_i32 s60, 1
	s_cselect_b32 s26, -2, 3
	s_add_i32 s26, s26, s60
	s_lshl_b32 s26, s26, 15
	s_add_i32 s26, s26, s36
	s_mov_b32 m0, s26
	v_lshl_add_u64 v[200:201], v[164:165], 0, s[0:1]
	global_load_lds_dwordx4 v[200:201], off
	s_mov_b32 m0, s30
	v_lshl_add_u64 v[200:201], v[200:201], 0, 64
	global_load_lds_dwordx4 v[200:201], off
	s_add_u32 m0, s26, 0x2000
	v_lshl_add_u64 v[200:201], v[162:163], 0, s[0:1]
	global_load_lds_dwordx4 v[200:201], off
	s_add_u32 m0, s30, 0x2000
	v_lshl_add_u64 v[200:201], v[200:201], 0, 64
	global_load_lds_dwordx4 v[200:201], off
	s_add_u32 m0, s26, 0x4000
	v_lshl_add_u64 v[200:201], v[160:161], 0, s[0:1]
	global_load_lds_dwordx4 v[200:201], off
	s_add_u32 m0, s30, 0x4000
	v_lshl_add_u64 v[200:201], v[200:201], 0, 64
	global_load_lds_dwordx4 v[200:201], off
	s_add_u32 m0, s26, 0x6000
	v_lshl_add_u64 v[200:201], v[158:159], 0, s[0:1]
	global_load_lds_dwordx4 v[200:201], off
	s_add_u32 m0, s30, 0x6000
	v_lshl_add_u64 v[200:201], v[200:201], 0, 64
	global_load_lds_dwordx4 v[200:201], off
	s_add_u32 s0, s0, 64
	s_addc_u32 s1, s1, 0

.Lg2_Ew:
.Lg2_O:
	s_waitcnt lgkmcnt(0)
	s_barrier
	ds_read_b128 v[130:133], v254 offset:16384
	ds_read_b128 v[134:137], v254 offset:17408
	ds_read_b128 v[150:153], v64
	ds_read_b128 v[146:149], v64 offset:1024
	v_mfma_f32_16x16x32_bf16 v[102:105], v[246:249], v[202:205], v[102:105]
	v_mfma_f32_16x16x32_bf16 v[70:73], v[250:253], v[202:205], v[70:73]
	v_mfma_f32_16x16x32_bf16 v[36:39], v[138:141], v[202:205], v[36:39]
	v_mfma_f32_16x16x32_bf16 v[4:7], v[142:145], v[202:205], v[4:7]
	s_cmp_lt_u32 s25, s37
	s_cbranch_scc0 .Lg2_O_sa
	s_sub_u32 s0, s0, 64
	s_subb_u32 s1, s1, 0
	s_cmp_gt_i32 s79, 0
	s_cselect_b32 s28, -1, 4
	s_add_i32 s28, s28, s79
	s_lshl_b32 s28, s28, 15
	s_add_i32 s28, s28, s36
	s_cmp_gt_i32 s79, 1
	s_cselect_b32 s26, -2, 3
	s_add_i32 s26, s26, s79
	s_lshl_b32 s26, s26, 15
	s_add_i32 s26, s26, s36
	s_mov_b32 m0, s26
	v_lshl_add_u64 v[202:203], v[164:165], 0, s[0:1]
	global_load_lds_dwordx4 v[202:203], off
	s_mov_b32 m0, s28
	v_lshl_add_u64 v[202:203], v[202:203], 0, 64
	global_load_lds_dwordx4 v[202:203], off
	s_add_u32 m0, s26, 0x2000
	v_lshl_add_u64 v[202:203], v[162:163], 0, s[0:1]
	global_load_lds_dwordx4 v[202:203], off
	s_add_u32 m0, s28, 0x2000
	v_lshl_add_u64 v[202:203], v[202:203], 0, 64
	global_load_lds_dwordx4 v[202:203], off
	s_add_u32 m0, s26, 0x4000
	v_lshl_add_u64 v[202:203], v[160:161], 0, s[0:1]
	global_load_lds_dwordx4 v[202:203], off
	s_add_u32 m0, s28, 0x4000
	v_lshl_add_u64 v[202:203], v[202:203], 0, 64
	global_load_lds_dwordx4 v[202:203], off
	s_add_u32 m0, s26, 0x6000
	v_lshl_add_u64 v[202:203], v[158:159], 0, s[0:1]
	global_load_lds_dwordx4 v[202:203], off
	s_add_u32 m0, s28, 0x6000
	v_lshl_add_u64 v[202:203], v[202:203], 0, 64
	global_load_lds_dwordx4 v[202:203], off
	s_add_u32 s0, s0, 64
	s_addc_u32 s1, s1, 0
.Lg2_O_sa:
	v_mfma_f32_16x16x32_bf16 v[98:101], v[246:249], v[206:209], v[98:101]
	v_mfma_f32_16x16x32_bf16 v[66:69], v[250:253], v[206:209], v[66:69]
	v_mfma_f32_16x16x32_bf16 v[28:31], v[138:141], v[206:209], v[28:31]
	v_mfma_f32_16x16x32_bf16 v[0:3], v[142:145], v[206:209], v[0:3]
	ds_read_b128 v[138:141], v254 offset:18432
	ds_read_b128 v[142:145], v254 offset:19456
	ds_read_b128 v[202:205], v64 offset:2048
	ds_read_b128 v[206:209], v64 offset:3072
	s_waitcnt lgkmcnt(4)
	v_mfma_f32_16x16x32_bf16 v[126:129], v[130:133], v[150:153], v[126:129]
	v_mfma_f32_16x16x32_bf16 v[94:97], v[134:137], v[150:153], v[94:97]
	v_mfma_f32_16x16x32_bf16 v[122:125], v[130:133], v[146:149], v[122:125]
	v_mfma_f32_16x16x32_bf16 v[90:93], v[134:137], v[146:149], v[90:93]
	s_waitcnt lgkmcnt(2)
	v_mfma_f32_16x16x32_bf16 v[60:63], v[138:141], v[150:153], v[60:63]
	v_mfma_f32_16x16x32_bf16 v[32:35], v[142:145], v[150:153], v[32:35]
	v_mfma_f32_16x16x32_bf16 v[56:59], v[138:141], v[146:149], v[56:59]
	v_mfma_f32_16x16x32_bf16 v[24:27], v[142:145], v[146:149], v[24:27]
	s_waitcnt lgkmcnt(0)
	v_mfma_f32_16x16x32_bf16 v[118:121], v[130:133], v[202:205], v[118:121]
	ds_read_b128 v[146:149], v64 offset:4096
	ds_read_b128 v[150:153], v64 offset:5120
	v_mfma_f32_16x16x32_bf16 v[86:89], v[134:137], v[202:205], v[86:89]
	v_mfma_f32_16x16x32_bf16 v[52:55], v[138:141], v[202:205], v[52:55]
	v_mfma_f32_16x16x32_bf16 v[20:23], v[142:145], v[202:205], v[20:23]
	v_mfma_f32_16x16x32_bf16 v[114:117], v[130:133], v[206:209], v[114:117]
	v_mfma_f32_16x16x32_bf16 v[82:85], v[134:137], v[206:209], v[82:85]
	v_mfma_f32_16x16x32_bf16 v[48:51], v[138:141], v[206:209], v[48:51]
	v_mfma_f32_16x16x32_bf16 v[16:19], v[142:145], v[206:209], v[16:19]
	s_cmp_lt_u32 s25, s27
	s_cbranch_scc0 .Lg2_O_sb
	s_sub_u32 s0, s0, 64
	s_subb_u32 s1, s1, 0
	s_cmp_gt_i32 s79, 0
	s_cselect_b32 s28, -1, 4
	s_add_i32 s28, s28, s79
	s_lshl_b32 s28, s28, 15
	s_add_i32 s28, s28, s36
	s_cmp_gt_i32 s79, 1
	s_cselect_b32 s26, -2, 3
	s_add_i32 s26, s26, s79
	s_lshl_b32 s26, s26, 15
	s_add_i32 s26, s26, s36
	s_mov_b32 m0, s26
	v_lshl_add_u64 v[202:203], v[164:165], 0, s[0:1]
	global_load_lds_dwordx4 v[202:203], off
	s_mov_b32 m0, s28
	v_lshl_add_u64 v[202:203], v[202:203], 0, 64
	global_load_lds_dwordx4 v[202:203], off
	s_add_u32 m0, s26, 0x2000
	v_lshl_add_u64 v[202:203], v[162:163], 0, s[0:1]
	global_load_lds_dwordx4 v[202:203], off
	s_add_u32 m0, s28, 0x2000
	v_lshl_add_u64 v[202:203], v[202:203], 0, 64
	global_load_lds_dwordx4 v[202:203], off
	s_add_u32 m0, s26, 0x4000
	v_lshl_add_u64 v[202:203], v[160:161], 0, s[0:1]
	global_load_lds_dwordx4 v[202:203], off
	s_add_u32 m0, s28, 0x4000
	v_lshl_add_u64 v[202:203], v[202:203], 0, 64
	global_load_lds_dwordx4 v[202:203], off
	s_add_u32 m0, s26, 0x6000
	v_lshl_add_u64 v[202:203], v[158:159], 0, s[0:1]
	global_load_lds_dwordx4 v[202:203], off
	s_add_u32 m0, s28, 0x6000
	v_lshl_add_u64 v[202:203], v[202:203], 0, 64
	global_load_lds_dwordx4 v[202:203], off
	s_add_u32 s0, s0, 64
	s_addc_u32 s1, s1, 0

.Lg3_Ew:
.Lg3_O:
	s_waitcnt lgkmcnt(0)
	s_barrier
	ds_read_b128 v[130:133], v254 offset:16384
	ds_read_b128 v[134:137], v254 offset:17408
	ds_read_b128 v[150:153], v64
	ds_read_b128 v[146:149], v64 offset:1024
	v_mfma_f32_16x16x32_bf16 v[28:31], v[246:249], v[202:205], v[28:31]
	v_mfma_f32_16x16x32_bf16 v[24:27], v[250:253], v[202:205], v[24:27]
	v_mfma_f32_16x16x32_bf16 v[20:23], v[138:141], v[202:205], v[20:23]
	v_mfma_f32_16x16x32_bf16 v[16:19], v[142:145], v[202:205], v[16:19]
	s_cmp_lt_u32 s25, s45
	s_cbranch_scc0 .Lg3_O_sa
	s_sub_u32 s28, s28, 64
	s_subb_u32 s29, s29, 0
	s_cmp_gt_i32 s75, 0
	s_cselect_b32 s30, -1, 4
	s_add_i32 s30, s30, s75
	s_lshl_b32 s30, s30, 15
	s_add_i32 s30, s30, s44
	s_cmp_gt_i32 s75, 1
	s_cselect_b32 s26, -2, 3
	s_add_i32 s26, s26, s75
	s_lshl_b32 s26, s26, 15
	s_add_i32 s26, s26, s44
	s_mov_b32 m0, s26
	v_lshl_add_u64 v[202:203], v[164:165], 0, s[28:29]
	global_load_lds_dwordx4 v[202:203], off
	s_mov_b32 m0, s30
	v_lshl_add_u64 v[202:203], v[202:203], 0, 64
	global_load_lds_dwordx4 v[202:203], off
	s_add_u32 m0, s26, 0x2000
	v_lshl_add_u64 v[202:203], v[162:163], 0, s[28:29]
	global_load_lds_dwordx4 v[202:203], off
	s_add_u32 m0, s30, 0x2000
	v_lshl_add_u64 v[202:203], v[202:203], 0, 64
	global_load_lds_dwordx4 v[202:203], off
	s_add_u32 m0, s26, 0x4000
	v_lshl_add_u64 v[202:203], v[160:161], 0, s[28:29]
	global_load_lds_dwordx4 v[202:203], off
	s_add_u32 m0, s30, 0x4000
	v_lshl_add_u64 v[202:203], v[202:203], 0, 64
	global_load_lds_dwordx4 v[202:203], off
	s_add_u32 m0, s26, 0x6000
	v_lshl_add_u64 v[202:203], v[158:159], 0, s[28:29]
	global_load_lds_dwordx4 v[202:203], off
	s_add_u32 m0, s30, 0x6000
	v_lshl_add_u64 v[202:203], v[202:203], 0, 64
	global_load_lds_dwordx4 v[202:203], off
	s_add_u32 s28, s28, 64
	s_addc_u32 s29, s29, 0
.Lg3_O_sa:
	v_mfma_f32_16x16x32_bf16 v[12:15], v[246:249], v[206:209], v[12:15]
	v_mfma_f32_16x16x32_bf16 v[8:11], v[250:253], v[206:209], v[8:11]
	v_mfma_f32_16x16x32_bf16 v[4:7], v[138:141], v[206:209], v[4:7]
	v_mfma_f32_16x16x32_bf16 v[0:3], v[142:145], v[206:209], v[0:3]
	ds_read_b128 v[138:141], v254 offset:18432
	ds_read_b128 v[142:145], v254 offset:19456
	ds_read_b128 v[202:205], v64 offset:2048
	ds_read_b128 v[206:209], v64 offset:3072
	s_waitcnt lgkmcnt(4)
	v_mfma_f32_16x16x32_bf16 v[126:129], v[130:133], v[150:153], v[126:129]
	v_mfma_f32_16x16x32_bf16 v[122:125], v[134:137], v[150:153], v[122:125]
	v_mfma_f32_16x16x32_bf16 v[110:113], v[130:133], v[146:149], v[110:113]
	v_mfma_f32_16x16x32_bf16 v[106:109], v[134:137], v[146:149], v[106:109]
	s_waitcnt lgkmcnt(2)
	v_mfma_f32_16x16x32_bf16 v[118:121], v[138:141], v[150:153], v[118:121]
	v_mfma_f32_16x16x32_bf16 v[114:117], v[142:145], v[150:153], v[114:117]
	v_mfma_f32_16x16x32_bf16 v[102:105], v[138:141], v[146:149], v[102:105]
	v_mfma_f32_16x16x32_bf16 v[98:101], v[142:145], v[146:149], v[98:101]
	s_waitcnt lgkmcnt(0)
	v_mfma_f32_16x16x32_bf16 v[94:97], v[130:133], v[202:205], v[94:97]
	ds_read_b128 v[146:149], v64 offset:4096
	ds_read_b128 v[150:153], v64 offset:5120
	v_mfma_f32_16x16x32_bf16 v[90:93], v[134:137], v[202:205], v[90:93]
	v_mfma_f32_16x16x32_bf16 v[86:89], v[138:141], v[202:205], v[86:89]
	v_mfma_f32_16x16x32_bf16 v[82:85], v[142:145], v[202:205], v[82:85]
	v_mfma_f32_16x16x32_bf16 v[78:81], v[130:133], v[206:209], v[78:81]
	v_mfma_f32_16x16x32_bf16 v[74:77], v[134:137], v[206:209], v[74:77]
	v_mfma_f32_16x16x32_bf16 v[70:73], v[138:141], v[206:209], v[70:73]
	v_mfma_f32_16x16x32_bf16 v[66:69], v[142:145], v[206:209], v[66:69]
	s_cmp_lt_u32 s25, s27
	s_cbranch_scc0 .Lg3_O_sb
	s_sub_u32 s28, s28, 64
	s_subb_u32 s29, s29, 0
	s_cmp_gt_i32 s75, 0
	s_cselect_b32 s30, -1, 4
	s_add_i32 s30, s30, s75
	s_lshl_b32 s30, s30, 15
	s_add_i32 s30, s30, s44
	s_cmp_gt_i32 s75, 1
	s_cselect_b32 s26, -2, 3
	s_add_i32 s26, s26, s75
	s_lshl_b32 s26, s26, 15
	s_add_i32 s26, s26, s44
	s_mov_b32 m0, s26
	v_lshl_add_u64 v[202:203], v[164:165], 0, s[28:29]
	global_load_lds_dwordx4 v[202:203], off
	s_mov_b32 m0, s30
	v_lshl_add_u64 v[202:203], v[202:203], 0, 64
	global_load_lds_dwordx4 v[202:203], off
	s_add_u32 m0, s26, 0x2000
	v_lshl_add_u64 v[202:203], v[162:163], 0, s[28:29]
	global_load_lds_dwordx4 v[202:203], off
	s_add_u32 m0, s30, 0x2000
	v_lshl_add_u64 v[202:203], v[202:203], 0, 64
	global_load_lds_dwordx4 v[202:203], off
	s_add_u32 m0, s26, 0x4000
	v_lshl_add_u64 v[202:203], v[160:161], 0, s[28:29]
	global_load_lds_dwordx4 v[202:203], off
	s_add_u32 m0, s30, 0x4000
	v_lshl_add_u64 v[202:203], v[202:203], 0, 64
	global_load_lds_dwordx4 v[202:203], off
	s_add_u32 m0, s26, 0x6000
	v_lshl_add_u64 v[202:203], v[158:159], 0, s[28:29]
	global_load_lds_dwordx4 v[202:203], off
	s_add_u32 m0, s30, 0x6000
	v_lshl_add_u64 v[202:203], v[202:203], 0, 64
	global_load_lds_dwordx4 v[202:203], off
	s_add_u32 s28, s28, 64
	s_addc_u32 s29, s29, 0

.Lg4_Ew:
.Lg4_O:
	s_waitcnt lgkmcnt(0)
	s_barrier
	ds_read_b128 v[130:133], v254 offset:16384
	ds_read_b128 v[134:137], v254 offset:17408
	ds_read_b128 v[150:153], v64
	ds_read_b128 v[146:149], v64 offset:1024
	v_mfma_f32_16x16x32_bf16 v[24:27], v[246:249], v[202:205], v[24:27]
	v_mfma_f32_16x16x32_bf16 v[20:23], v[250:253], v[202:205], v[20:23]
	v_mfma_f32_16x16x32_bf16 v[16:19], v[138:141], v[202:205], v[16:19]
	v_mfma_f32_16x16x32_bf16 v[12:15], v[142:145], v[202:205], v[12:15]
	s_cmp_lt_u32 s75, s41
	s_cbranch_scc0 .Lg4_O_sa
	s_sub_u32 s28, s28, 64
	s_subb_u32 s29, s29, 0
	s_cmp_gt_i32 s1, 0
	s_cselect_b32 s30, -1, 4
	s_add_i32 s30, s30, s1
	s_lshl_b32 s30, s30, 15
	s_add_i32 s30, s30, s40
	s_cmp_gt_i32 s1, 1
	s_cselect_b32 s26, -2, 3
	s_add_i32 s26, s26, s1
	s_lshl_b32 s26, s26, 15
	s_add_i32 s26, s26, s40
	s_mov_b32 m0, s26
	v_lshl_add_u64 v[202:203], v[164:165], 0, s[28:29]
	global_load_lds_dwordx4 v[202:203], off
	s_mov_b32 m0, s30
	v_lshl_add_u64 v[202:203], v[202:203], 0, 64
	global_load_lds_dwordx4 v[202:203], off
	s_add_u32 m0, s26, 0x2000
	v_lshl_add_u64 v[202:203], v[162:163], 0, s[28:29]
	global_load_lds_dwordx4 v[202:203], off
	s_add_u32 m0, s30, 0x2000
	v_lshl_add_u64 v[202:203], v[202:203], 0, 64
	global_load_lds_dwordx4 v[202:203], off
	s_add_u32 m0, s26, 0x4000
	v_lshl_add_u64 v[202:203], v[160:161], 0, s[28:29]
	global_load_lds_dwordx4 v[202:203], off
	s_add_u32 m0, s30, 0x4000
	v_lshl_add_u64 v[202:203], v[202:203], 0, 64
	global_load_lds_dwordx4 v[202:203], off
	s_add_u32 m0, s26, 0x6000
	v_lshl_add_u64 v[202:203], v[158:159], 0, s[28:29]
	global_load_lds_dwordx4 v[202:203], off
	s_add_u32 m0, s30, 0x6000
	v_lshl_add_u64 v[202:203], v[202:203], 0, 64
	global_load_lds_dwordx4 v[202:203], off
	s_add_u32 s28, s28, 64
	s_addc_u32 s29, s29, 0
.Lg4_O_sa:
	v_mfma_f32_16x16x32_bf16 v[8:11], v[246:249], v[206:209], v[8:11]
	v_mfma_f32_16x16x32_bf16 v[4:7], v[250:253], v[206:209], v[4:7]
	v_mfma_f32_16x16x32_bf16 v[0:3], v[138:141], v[206:209], v[0:3]
	v_mfma_f32_16x16x32_bf16 v[28:31], v[142:145], v[206:209], v[28:31]
	ds_read_b128 v[138:141], v254 offset:18432
	ds_read_b128 v[142:145], v254 offset:19456
	ds_read_b128 v[202:205], v64 offset:2048
	ds_read_b128 v[206:209], v64 offset:3072
	s_waitcnt lgkmcnt(4)
	v_mfma_f32_16x16x32_bf16 v[126:129], v[130:133], v[150:153], v[126:129]
	v_mfma_f32_16x16x32_bf16 v[122:125], v[134:137], v[150:153], v[122:125]
	v_mfma_f32_16x16x32_bf16 v[110:113], v[130:133], v[146:149], v[110:113]
	v_mfma_f32_16x16x32_bf16 v[106:109], v[134:137], v[146:149], v[106:109]
	s_waitcnt lgkmcnt(2)
	v_mfma_f32_16x16x32_bf16 v[118:121], v[138:141], v[150:153], v[118:121]
	v_mfma_f32_16x16x32_bf16 v[114:117], v[142:145], v[150:153], v[114:117]
	v_mfma_f32_16x16x32_bf16 v[102:105], v[138:141], v[146:149], v[102:105]
	v_mfma_f32_16x16x32_bf16 v[98:101], v[142:145], v[146:149], v[98:101]
	s_waitcnt lgkmcnt(0)
	v_mfma_f32_16x16x32_bf16 v[94:97], v[130:133], v[202:205], v[94:97]
	ds_read_b128 v[146:149], v64 offset:4096
	ds_read_b128 v[150:153], v64 offset:5120
	v_mfma_f32_16x16x32_bf16 v[90:93], v[134:137], v[202:205], v[90:93]
	v_mfma_f32_16x16x32_bf16 v[86:89], v[138:141], v[202:205], v[86:89]
	v_mfma_f32_16x16x32_bf16 v[82:85], v[142:145], v[202:205], v[82:85]
	v_mfma_f32_16x16x32_bf16 v[78:81], v[130:133], v[206:209], v[78:81]
	v_mfma_f32_16x16x32_bf16 v[74:77], v[134:137], v[206:209], v[74:77]
	v_mfma_f32_16x16x32_bf16 v[70:73], v[138:141], v[206:209], v[70:73]
	v_mfma_f32_16x16x32_bf16 v[66:69], v[142:145], v[206:209], v[66:69]
	s_cmp_lt_u32 s75, s27
	s_cbranch_scc0 .Lg4_O_sb
	s_sub_u32 s28, s28, 64
	s_subb_u32 s29, s29, 0
	s_cmp_gt_i32 s1, 0
	s_cselect_b32 s30, -1, 4
	s_add_i32 s30, s30, s1
	s_lshl_b32 s30, s30, 15
	s_add_i32 s30, s30, s40
	s_cmp_gt_i32 s1, 1
	s_cselect_b32 s26, -2, 3
	s_add_i32 s26, s26, s1
	s_lshl_b32 s26, s26, 15
	s_add_i32 s26, s26, s40
	s_mov_b32 m0, s26
	v_lshl_add_u64 v[202:203], v[164:165], 0, s[28:29]
	global_load_lds_dwordx4 v[202:203], off
	s_mov_b32 m0, s30
	v_lshl_add_u64 v[202:203], v[202:203], 0, 64
	global_load_lds_dwordx4 v[202:203], off
	s_add_u32 m0, s26, 0x2000
	v_lshl_add_u64 v[202:203], v[162:163], 0, s[28:29]
	global_load_lds_dwordx4 v[202:203], off
	s_add_u32 m0, s30, 0x2000
	v_lshl_add_u64 v[202:203], v[202:203], 0, 64
	global_load_lds_dwordx4 v[202:203], off
	s_add_u32 m0, s26, 0x4000
	v_lshl_add_u64 v[202:203], v[160:161], 0, s[28:29]
	global_load_lds_dwordx4 v[202:203], off
	s_add_u32 m0, s30, 0x4000
	v_lshl_add_u64 v[202:203], v[202:203], 0, 64
	global_load_lds_dwordx4 v[202:203], off
	s_add_u32 m0, s26, 0x6000
	v_lshl_add_u64 v[202:203], v[158:159], 0, s[28:29]
	global_load_lds_dwordx4 v[202:203], off
	s_add_u32 m0, s30, 0x6000
	v_lshl_add_u64 v[202:203], v[202:203], 0, 64
	global_load_lds_dwordx4 v[202:203], off
	s_add_u32 s28, s28, 64
	s_addc_u32 s29, s29, 0

.Lg5_Ew:
.Lg5_O:
	s_waitcnt lgkmcnt(0)
	s_barrier
	ds_read_b128 v[130:133], v254 offset:16384
	ds_read_b128 v[134:137], v254 offset:17408
	ds_read_b128 v[150:153], v64
	ds_read_b128 v[146:149], v64 offset:1024
	v_mfma_f32_16x16x32_bf16 v[28:31], v[246:249], v[202:205], v[28:31]
	v_mfma_f32_16x16x32_bf16 v[24:27], v[250:253], v[202:205], v[24:27]
	v_mfma_f32_16x16x32_bf16 v[20:23], v[138:141], v[202:205], v[20:23]
	v_mfma_f32_16x16x32_bf16 v[16:19], v[142:145], v[202:205], v[16:19]
	s_cmp_lt_u32 s41, s29
	s_cbranch_scc0 .Lg5_O_sa
	s_sub_u32 s0, s0, 64
	s_subb_u32 s1, s1, 0
	s_cmp_gt_i32 s65, 0
	s_cselect_b32 s26, -1, 4
	s_add_i32 s26, s26, s65
	s_lshl_b32 s26, s26, 15
	s_add_i32 s26, s26, s28
	s_cmp_gt_i32 s65, 1
	s_cselect_b32 s24, -2, 3
	s_add_i32 s24, s24, s65
	s_lshl_b32 s24, s24, 15
	s_add_i32 s24, s24, s28
	s_mov_b32 m0, s24
	v_lshl_add_u64 v[202:203], v[164:165], 0, s[0:1]
	global_load_lds_dwordx4 v[202:203], off
	s_mov_b32 m0, s26
	v_lshl_add_u64 v[202:203], v[202:203], 0, 64
	global_load_lds_dwordx4 v[202:203], off
	s_add_u32 m0, s24, 0x2000
	v_lshl_add_u64 v[202:203], v[162:163], 0, s[0:1]
	global_load_lds_dwordx4 v[202:203], off
	s_add_u32 m0, s26, 0x2000
	v_lshl_add_u64 v[202:203], v[202:203], 0, 64
	global_load_lds_dwordx4 v[202:203], off
	s_add_u32 m0, s24, 0x4000
	v_lshl_add_u64 v[202:203], v[160:161], 0, s[0:1]
	global_load_lds_dwordx4 v[202:203], off
	s_add_u32 m0, s26, 0x4000
	v_lshl_add_u64 v[202:203], v[202:203], 0, 64
	global_load_lds_dwordx4 v[202:203], off
	s_add_u32 m0, s24, 0x6000
	v_lshl_add_u64 v[202:203], v[158:159], 0, s[0:1]
	global_load_lds_dwordx4 v[202:203], off
	s_add_u32 m0, s26, 0x6000
	v_lshl_add_u64 v[202:203], v[202:203], 0, 64
	global_load_lds_dwordx4 v[202:203], off
	s_add_u32 s0, s0, 64
	s_addc_u32 s1, s1, 0
.Lg5_O_sa:
	v_mfma_f32_16x16x32_bf16 v[12:15], v[246:249], v[206:209], v[12:15]
	v_mfma_f32_16x16x32_bf16 v[8:11], v[250:253], v[206:209], v[8:11]
	v_mfma_f32_16x16x32_bf16 v[4:7], v[138:141], v[206:209], v[4:7]
	v_mfma_f32_16x16x32_bf16 v[0:3], v[142:145], v[206:209], v[0:3]
	ds_read_b128 v[138:141], v254 offset:18432
	ds_read_b128 v[142:145], v254 offset:19456
	ds_read_b128 v[202:205], v64 offset:2048
	ds_read_b128 v[206:209], v64 offset:3072
	s_waitcnt lgkmcnt(4)
	v_mfma_f32_16x16x32_bf16 v[126:129], v[130:133], v[150:153], v[126:129]
	v_mfma_f32_16x16x32_bf16 v[122:125], v[134:137], v[150:153], v[122:125]
	v_mfma_f32_16x16x32_bf16 v[110:113], v[130:133], v[146:149], v[110:113]
	v_mfma_f32_16x16x32_bf16 v[106:109], v[134:137], v[146:149], v[106:109]
	s_waitcnt lgkmcnt(2)
	v_mfma_f32_16x16x32_bf16 v[118:121], v[138:141], v[150:153], v[118:121]
	v_mfma_f32_16x16x32_bf16 v[114:117], v[142:145], v[150:153], v[114:117]
	v_mfma_f32_16x16x32_bf16 v[102:105], v[138:141], v[146:149], v[102:105]
	v_mfma_f32_16x16x32_bf16 v[98:101], v[142:145], v[146:149], v[98:101]
	s_waitcnt lgkmcnt(0)
	v_mfma_f32_16x16x32_bf16 v[94:97], v[130:133], v[202:205], v[94:97]
	ds_read_b128 v[146:149], v64 offset:4096
	ds_read_b128 v[150:153], v64 offset:5120
	v_mfma_f32_16x16x32_bf16 v[90:93], v[134:137], v[202:205], v[90:93]
	v_mfma_f32_16x16x32_bf16 v[86:89], v[138:141], v[202:205], v[86:89]
	v_mfma_f32_16x16x32_bf16 v[82:85], v[142:145], v[202:205], v[82:85]
	v_mfma_f32_16x16x32_bf16 v[78:81], v[130:133], v[206:209], v[78:81]
	v_mfma_f32_16x16x32_bf16 v[74:77], v[134:137], v[206:209], v[74:77]
	v_mfma_f32_16x16x32_bf16 v[70:73], v[138:141], v[206:209], v[70:73]
	v_mfma_f32_16x16x32_bf16 v[66:69], v[142:145], v[206:209], v[66:69]
	s_cmp_lt_u32 s41, s25
	s_cbranch_scc0 .Lg5_O_sb
	s_sub_u32 s0, s0, 64
	s_subb_u32 s1, s1, 0
	s_cmp_gt_i32 s65, 0
	s_cselect_b32 s26, -1, 4
	s_add_i32 s26, s26, s65
	s_lshl_b32 s26, s26, 15
	s_add_i32 s26, s26, s28
	s_cmp_gt_i32 s65, 1
	s_cselect_b32 s24, -2, 3
	s_add_i32 s24, s24, s65
	s_lshl_b32 s24, s24, 15
	s_add_i32 s24, s24, s28
	s_mov_b32 m0, s24
	v_lshl_add_u64 v[202:203], v[164:165], 0, s[0:1]
	global_load_lds_dwordx4 v[202:203], off
	s_mov_b32 m0, s26
	v_lshl_add_u64 v[202:203], v[202:203], 0, 64
	global_load_lds_dwordx4 v[202:203], off
	s_add_u32 m0, s24, 0x2000
	v_lshl_add_u64 v[202:203], v[162:163], 0, s[0:1]
	global_load_lds_dwordx4 v[202:203], off
	s_add_u32 m0, s26, 0x2000
	v_lshl_add_u64 v[202:203], v[202:203], 0, 64
	global_load_lds_dwordx4 v[202:203], off
	s_add_u32 m0, s24, 0x4000
	v_lshl_add_u64 v[202:203], v[160:161], 0, s[0:1]
	global_load_lds_dwordx4 v[202:203], off
	s_add_u32 m0, s26, 0x4000
	v_lshl_add_u64 v[202:203], v[202:203], 0, 64
	global_load_lds_dwordx4 v[202:203], off
	s_add_u32 m0, s24, 0x6000
	v_lshl_add_u64 v[202:203], v[158:159], 0, s[0:1]
	global_load_lds_dwordx4 v[202:203], off
	s_add_u32 m0, s26, 0x6000
	v_lshl_add_u64 v[202:203], v[202:203], 0, 64
	global_load_lds_dwordx4 v[202:203], off
	s_add_u32 s0, s0, 64
	s_addc_u32 s1, s1, 0

.Lg6_Ew:
.Lg6_O:
	s_waitcnt lgkmcnt(0)
	s_barrier
	ds_read_b128 v[130:133], v254 offset:16384
	ds_read_b128 v[134:137], v254 offset:17408
	ds_read_b128 v[150:153], v64
	ds_read_b128 v[146:149], v64 offset:1024
	v_mfma_f32_16x16x32_bf16 v[28:31], v[246:249], v[202:205], v[28:31]
	v_mfma_f32_16x16x32_bf16 v[24:27], v[250:253], v[202:205], v[24:27]
	v_mfma_f32_16x16x32_bf16 v[20:23], v[138:141], v[202:205], v[20:23]
	v_mfma_f32_16x16x32_bf16 v[16:19], v[142:145], v[202:205], v[16:19]
	s_cmp_lt_u32 s1, s41
	s_cbranch_scc0 .Lg6_O_sa
	s_sub_u32 s28, s28, 64
	s_subb_u32 s29, s29, 0
	s_cmp_gt_i32 s65, 0
	s_cselect_b32 s27, -1, 4
	s_add_i32 s27, s27, s65
	s_lshl_b32 s27, s27, 15
	s_add_i32 s27, s27, s40
	s_cmp_gt_i32 s65, 1
	s_cselect_b32 s25, -2, 3
	s_add_i32 s25, s25, s65
	s_lshl_b32 s25, s25, 15
	s_add_i32 s25, s25, s40
	s_mov_b32 m0, s25
	v_lshl_add_u64 v[202:203], v[164:165], 0, s[28:29]
	global_load_lds_dwordx4 v[202:203], off
	s_mov_b32 m0, s27
	v_lshl_add_u64 v[202:203], v[202:203], 0, 64
	global_load_lds_dwordx4 v[202:203], off
	s_add_u32 m0, s25, 0x2000
	v_lshl_add_u64 v[202:203], v[162:163], 0, s[28:29]
	global_load_lds_dwordx4 v[202:203], off
	s_add_u32 m0, s27, 0x2000
	v_lshl_add_u64 v[202:203], v[202:203], 0, 64
	global_load_lds_dwordx4 v[202:203], off
	s_add_u32 m0, s25, 0x4000
	v_lshl_add_u64 v[202:203], v[160:161], 0, s[28:29]
	global_load_lds_dwordx4 v[202:203], off
	s_add_u32 m0, s27, 0x4000
	v_lshl_add_u64 v[202:203], v[202:203], 0, 64
	global_load_lds_dwordx4 v[202:203], off
	s_add_u32 m0, s25, 0x6000
	v_lshl_add_u64 v[202:203], v[158:159], 0, s[28:29]
	global_load_lds_dwordx4 v[202:203], off
	s_add_u32 m0, s27, 0x6000
	v_lshl_add_u64 v[202:203], v[202:203], 0, 64
	global_load_lds_dwordx4 v[202:203], off
	s_add_u32 s28, s28, 64
	s_addc_u32 s29, s29, 0
.Lg6_O_sa:
	v_mfma_f32_16x16x32_bf16 v[12:15], v[246:249], v[206:209], v[12:15]
	v_mfma_f32_16x16x32_bf16 v[8:11], v[250:253], v[206:209], v[8:11]
	v_mfma_f32_16x16x32_bf16 v[4:7], v[138:141], v[206:209], v[4:7]
	v_mfma_f32_16x16x32_bf16 v[0:3], v[142:145], v[206:209], v[0:3]
	ds_read_b128 v[138:141], v254 offset:18432
	ds_read_b128 v[142:145], v254 offset:19456
	ds_read_b128 v[202:205], v64 offset:2048
	ds_read_b128 v[206:209], v64 offset:3072
	s_waitcnt lgkmcnt(4)
	v_mfma_f32_16x16x32_bf16 v[126:129], v[130:133], v[150:153], v[126:129]
	v_mfma_f32_16x16x32_bf16 v[122:125], v[134:137], v[150:153], v[122:125]
	v_mfma_f32_16x16x32_bf16 v[110:113], v[130:133], v[146:149], v[110:113]
	v_mfma_f32_16x16x32_bf16 v[106:109], v[134:137], v[146:149], v[106:109]
	s_waitcnt lgkmcnt(2)
	v_mfma_f32_16x16x32_bf16 v[118:121], v[138:141], v[150:153], v[118:121]
	v_mfma_f32_16x16x32_bf16 v[114:117], v[142:145], v[150:153], v[114:117]
	v_mfma_f32_16x16x32_bf16 v[102:105], v[138:141], v[146:149], v[102:105]
	v_mfma_f32_16x16x32_bf16 v[98:101], v[142:145], v[146:149], v[98:101]
	s_waitcnt lgkmcnt(0)
	v_mfma_f32_16x16x32_bf16 v[94:97], v[130:133], v[202:205], v[94:97]
	ds_read_b128 v[146:149], v64 offset:4096
	ds_read_b128 v[150:153], v64 offset:5120
	v_mfma_f32_16x16x32_bf16 v[90:93], v[134:137], v[202:205], v[90:93]
	v_mfma_f32_16x16x32_bf16 v[86:89], v[138:141], v[202:205], v[86:89]
	v_mfma_f32_16x16x32_bf16 v[82:85], v[142:145], v[202:205], v[82:85]
	v_mfma_f32_16x16x32_bf16 v[78:81], v[130:133], v[206:209], v[78:81]
	v_mfma_f32_16x16x32_bf16 v[74:77], v[134:137], v[206:209], v[74:77]
	v_mfma_f32_16x16x32_bf16 v[70:73], v[138:141], v[206:209], v[70:73]
	v_mfma_f32_16x16x32_bf16 v[66:69], v[142:145], v[206:209], v[66:69]
	s_cmp_lt_u32 s1, s26
	s_cbranch_scc0 .Lg6_O_sb
	s_sub_u32 s28, s28, 64
	s_subb_u32 s29, s29, 0
	s_cmp_gt_i32 s65, 0
	s_cselect_b32 s27, -1, 4
	s_add_i32 s27, s27, s65
	s_lshl_b32 s27, s27, 15
	s_add_i32 s27, s27, s40
	s_cmp_gt_i32 s65, 1
	s_cselect_b32 s25, -2, 3
	s_add_i32 s25, s25, s65
	s_lshl_b32 s25, s25, 15
	s_add_i32 s25, s25, s40
	s_mov_b32 m0, s25
	v_lshl_add_u64 v[202:203], v[164:165], 0, s[28:29]
	global_load_lds_dwordx4 v[202:203], off
	s_mov_b32 m0, s27
	v_lshl_add_u64 v[202:203], v[202:203], 0, 64
	global_load_lds_dwordx4 v[202:203], off
	s_add_u32 m0, s25, 0x2000
	v_lshl_add_u64 v[202:203], v[162:163], 0, s[28:29]
	global_load_lds_dwordx4 v[202:203], off
	s_add_u32 m0, s27, 0x2000
	v_lshl_add_u64 v[202:203], v[202:203], 0, 64
	global_load_lds_dwordx4 v[202:203], off
	s_add_u32 m0, s25, 0x4000
	v_lshl_add_u64 v[202:203], v[160:161], 0, s[28:29]
	global_load_lds_dwordx4 v[202:203], off
	s_add_u32 m0, s27, 0x4000
	v_lshl_add_u64 v[202:203], v[202:203], 0, 64
	global_load_lds_dwordx4 v[202:203], off
	s_add_u32 m0, s25, 0x6000
	v_lshl_add_u64 v[202:203], v[158:159], 0, s[28:29]
	global_load_lds_dwordx4 v[202:203], off
	s_add_u32 m0, s27, 0x6000
	v_lshl_add_u64 v[202:203], v[202:203], 0, 64
	global_load_lds_dwordx4 v[202:203], off
	s_add_u32 s28, s28, 64
	s_addc_u32 s29, s29, 0

.Lg7_Ew:
.Lg7_O:
	s_waitcnt lgkmcnt(0)
	s_barrier
	ds_read_b128 v[130:133], v254 offset:16384
	ds_read_b128 v[134:137], v254 offset:17408
	ds_read_b128 v[150:153], v64
	ds_read_b128 v[146:149], v64 offset:1024
	v_mfma_f32_16x16x32_bf16 v[28:31], v[246:249], v[202:205], v[28:31]
	v_mfma_f32_16x16x32_bf16 v[24:27], v[250:253], v[202:205], v[24:27]
	v_mfma_f32_16x16x32_bf16 v[20:23], v[138:141], v[202:205], v[20:23]
	v_mfma_f32_16x16x32_bf16 v[16:19], v[142:145], v[202:205], v[16:19]
	s_cmp_lt_u32 s45, s31
	s_cbranch_scc0 .Lg7_O_sa
	s_sub_u32 s0, s0, 64
	s_subb_u32 s1, s1, 0
	s_cmp_gt_i32 s41, 0
	s_cselect_b32 s28, -1, 4
	s_add_i32 s28, s28, s41
	s_lshl_b32 s28, s28, 15
	s_add_i32 s28, s28, s30
	s_cmp_gt_i32 s41, 1
	s_cselect_b32 s26, -2, 3
	s_add_i32 s26, s26, s41
	s_lshl_b32 s26, s26, 15
	s_add_i32 s26, s26, s30
	s_mov_b32 m0, s26
	v_lshl_add_u64 v[202:203], v[164:165], 0, s[0:1]
	global_load_lds_dwordx4 v[202:203], off
	s_mov_b32 m0, s28
	v_lshl_add_u64 v[202:203], v[202:203], 0, 64
	global_load_lds_dwordx4 v[202:203], off
	s_add_u32 m0, s26, 0x2000
	v_lshl_add_u64 v[202:203], v[162:163], 0, s[0:1]
	global_load_lds_dwordx4 v[202:203], off
	s_add_u32 m0, s28, 0x2000
	v_lshl_add_u64 v[202:203], v[202:203], 0, 64
	global_load_lds_dwordx4 v[202:203], off
	s_add_u32 m0, s26, 0x4000
	v_lshl_add_u64 v[202:203], v[160:161], 0, s[0:1]
	global_load_lds_dwordx4 v[202:203], off
	s_add_u32 m0, s28, 0x4000
	v_lshl_add_u64 v[202:203], v[202:203], 0, 64
	global_load_lds_dwordx4 v[202:203], off
	s_add_u32 m0, s26, 0x6000
	v_lshl_add_u64 v[202:203], v[158:159], 0, s[0:1]
	global_load_lds_dwordx4 v[202:203], off
	s_add_u32 m0, s28, 0x6000
	v_lshl_add_u64 v[202:203], v[202:203], 0, 64
	global_load_lds_dwordx4 v[202:203], off
	s_add_u32 s0, s0, 64
	s_addc_u32 s1, s1, 0
.Lg7_O_sa:
	v_mfma_f32_16x16x32_bf16 v[12:15], v[246:249], v[206:209], v[12:15]
	v_mfma_f32_16x16x32_bf16 v[8:11], v[250:253], v[206:209], v[8:11]
	v_mfma_f32_16x16x32_bf16 v[4:7], v[138:141], v[206:209], v[4:7]
	v_mfma_f32_16x16x32_bf16 v[0:3], v[142:145], v[206:209], v[0:3]
	ds_read_b128 v[138:141], v254 offset:18432
	ds_read_b128 v[142:145], v254 offset:19456
	ds_read_b128 v[202:205], v64 offset:2048
	ds_read_b128 v[206:209], v64 offset:3072
	s_waitcnt lgkmcnt(4)
	v_mfma_f32_16x16x32_bf16 v[126:129], v[130:133], v[150:153], v[126:129]
	v_mfma_f32_16x16x32_bf16 v[122:125], v[134:137], v[150:153], v[122:125]
	v_mfma_f32_16x16x32_bf16 v[110:113], v[130:133], v[146:149], v[110:113]
	v_mfma_f32_16x16x32_bf16 v[106:109], v[134:137], v[146:149], v[106:109]
	s_waitcnt lgkmcnt(2)
	v_mfma_f32_16x16x32_bf16 v[118:121], v[138:141], v[150:153], v[118:121]
	v_mfma_f32_16x16x32_bf16 v[114:117], v[142:145], v[150:153], v[114:117]
	v_mfma_f32_16x16x32_bf16 v[102:105], v[138:141], v[146:149], v[102:105]
	v_mfma_f32_16x16x32_bf16 v[98:101], v[142:145], v[146:149], v[98:101]
	s_waitcnt lgkmcnt(0)
	v_mfma_f32_16x16x32_bf16 v[94:97], v[130:133], v[202:205], v[94:97]
	ds_read_b128 v[146:149], v64 offset:4096
	ds_read_b128 v[150:153], v64 offset:5120
	v_mfma_f32_16x16x32_bf16 v[90:93], v[134:137], v[202:205], v[90:93]
	v_mfma_f32_16x16x32_bf16 v[86:89], v[138:141], v[202:205], v[86:89]
	v_mfma_f32_16x16x32_bf16 v[82:85], v[142:145], v[202:205], v[82:85]
	v_mfma_f32_16x16x32_bf16 v[78:81], v[130:133], v[206:209], v[78:81]
	v_mfma_f32_16x16x32_bf16 v[74:77], v[134:137], v[206:209], v[74:77]
	v_mfma_f32_16x16x32_bf16 v[70:73], v[138:141], v[206:209], v[70:73]
	v_mfma_f32_16x16x32_bf16 v[66:69], v[142:145], v[206:209], v[66:69]
	s_cmp_lt_u32 s45, s27
	s_cbranch_scc0 .Lg7_O_sb
	s_sub_u32 s0, s0, 64
	s_subb_u32 s1, s1, 0
	s_cmp_gt_i32 s41, 0
	s_cselect_b32 s28, -1, 4
	s_add_i32 s28, s28, s41
	s_lshl_b32 s28, s28, 15
	s_add_i32 s28, s28, s30
	s_cmp_gt_i32 s41, 1
	s_cselect_b32 s26, -2, 3
	s_add_i32 s26, s26, s41
	s_lshl_b32 s26, s26, 15
	s_add_i32 s26, s26, s30
	s_mov_b32 m0, s26
	v_lshl_add_u64 v[202:203], v[164:165], 0, s[0:1]
	global_load_lds_dwordx4 v[202:203], off
	s_mov_b32 m0, s28
	v_lshl_add_u64 v[202:203], v[202:203], 0, 64
	global_load_lds_dwordx4 v[202:203], off
	s_add_u32 m0, s26, 0x2000
	v_lshl_add_u64 v[202:203], v[162:163], 0, s[0:1]
	global_load_lds_dwordx4 v[202:203], off
	s_add_u32 m0, s28, 0x2000
	v_lshl_add_u64 v[202:203], v[202:203], 0, 64
	global_load_lds_dwordx4 v[202:203], off
	s_add_u32 m0, s26, 0x4000
	v_lshl_add_u64 v[202:203], v[160:161], 0, s[0:1]
	global_load_lds_dwordx4 v[202:203], off
	s_add_u32 m0, s28, 0x4000
	v_lshl_add_u64 v[202:203], v[202:203], 0, 64
	global_load_lds_dwordx4 v[202:203], off
	s_add_u32 m0, s26, 0x6000
	v_lshl_add_u64 v[202:203], v[158:159], 0, s[0:1]
	global_load_lds_dwordx4 v[202:203], off
	s_add_u32 m0, s28, 0x6000
	v_lshl_add_u64 v[202:203], v[202:203], 0, 64
	global_load_lds_dwordx4 v[202:203], off
	s_add_u32 s0, s0, 64
	s_addc_u32 s1, s1, 0
